# fill_rs_table: 4 row-stat loads issued together (3 phases); prologue c8t table spread over 16 waves instead of 16 serial iterations on one wave; plus previous stack
# speedup vs baseline: 1.0306x; 1.0105x over previous
; __device__ __forceinline__ void prologue(const Params& p, LAS unsigned char* lds, int gw, int ngw, int wave, int lane) {
;     ...
;     if (gw == 0) { float* c8t = (float*)(ws + WS_C8);
;         for (int i = lane; i < DM; i += 64) { const float l = p.in[10][i]; c8t[i] = -8.0f * (fmaxf(-l, 0.f) + log1pf(expf(-fabsf(l)))); } }
.LBB0_29:
	s_cmp_gt_u32 s76, 15
	s_cbranch_scc1 .LBB0_34
	v_lshl_add_u32 v44, s76, 6, v2
	s_movk_i32 s0, 0x400
	v_cmp_gt_i32_e32 vcc, s0, v44
	s_and_saveexec_b64 s[0:1], vcc
	s_cbranch_execz .LBB0_33
	v_ashrrev_i32_e32 v45, 31, v44
	v_readlane_b32 s56, v250, 2
	v_lshlrev_b64 v[6:7], 2, v[44:45]
	v_readlane_b32 s60, v250, 6
	v_readlane_b32 s61, v250, 7
	s_mov_b64 s[4:5], 0x3900000
	v_subrev_u32_e32 v10, 64, v44
	v_lshl_add_u64 v[4:5], s[60:61], 0, v[6:7]
	v_lshl_add_u64 v[6:7], s[90:91], 0, v[6:7]
	v_lshl_add_u64 v[6:7], v[6:7], 0, s[4:5]
	s_mov_b64 s[4:5], 0
	s_mov_b32 s10, 0xbfb8aa3b
	s_mov_b32 s11, 0xb2a5705f
	s_mov_b32 s18, 0x42ce8ed0
	s_mov_b32 s19, 0xc2b17218
	s_mov_b32 s24, 0x7f800000
	v_mov_b32_e32 v3, 0x7f800000
	s_mov_b32 s25, 0x3f2aaaab
	v_mov_b32_e32 v11, 0x3ecc95a3
	s_mov_b32 s30, 0x3f317218
	s_mov_b32 s31, 0x33800000
	s_mov_b64 s[6:7], 0x100
	s_movk_i32 s34, 0xffff
	v_mov_b32_e32 v8, 0x3f317218
	v_readlane_b32 s57, v250, 3
	v_readlane_b32 s58, v250, 4
	v_readlane_b32 s59, v250, 5
	v_readlane_b32 s62, v250, 8
	v_readlane_b32 s63, v250, 9
	v_readlane_b32 s64, v250, 10
	v_readlane_b32 s65, v250, 11
	v_readlane_b32 s66, v250, 12
	v_readlane_b32 s67, v250, 13
	v_readlane_b32 s68, v250, 14
	v_readlane_b32 s69, v250, 15
	v_readlane_b32 s70, v250, 16
	v_readlane_b32 s71, v250, 17

; #define LAS __attribute__((address_space(3)))
; __device__ __forceinline__ float row_rs(const float* ssp, int row) { const f32x4 s = *(const f32x4*)(ssp + (size_t)row * 4); return rsqrtf(((s[0] + s[1]) + (s[2] + s[3])) * (1.0f / DM) + RMS_EPS); }
; __device__ __forceinline__ int fill_rs_table(LAS unsigned char* lds, const float* ssp, const pg8::StaticOrder& S, int tid) {
;     pg8::Unit u0; const int row_base = S.next(0, u0) ? (u0.pm / pg8::WGM) * pg8::WGM * pg8::BM : 0;
;     LAS float* rst = (LAS float*)(lds + RST_OFF);
;     for (int i = tid; i < pg8::WGM * pg8::BM; i += NTHREADS) rst[i] = row_rs(ssp, row_base + i);
;     asm volatile("s_waitcnt lgkmcnt(0)" ::: "memory"); __syncthreads();
.LBB0_98:
	global_load_dwordx4 v[30:33], v[0:1], off
	v_lshl_add_u64 v[0:1], v[0:1], 0, s[18:19]
	global_load_dwordx4 v[34:37], v[0:1], off
	v_lshl_add_u64 v[0:1], v[0:1], 0, s[18:19]
	global_load_dwordx4 v[38:41], v[0:1], off
	v_lshl_add_u64 v[0:1], v[0:1], 0, s[18:19]
	global_load_dwordx4 v[42:45], v[0:1], off
	s_waitcnt vmcnt(3)
	v_mov_b32_e32 v46, v31
	v_mov_b32_e32 v47, v32
	v_mov_b32_e32 v31, v33
	v_pk_add_f32 v[30:31], v[46:47], v[30:31]
	s_nop 0
	v_add_f32_e32 v30, v30, v31
	v_fmamk_f32 v30, v30, 0x3a800000, v4
	v_mul_f32_e32 v31, 0x4b800000, v30
	v_cmp_gt_f32_e32 vcc, s0, v30
	s_nop 1
	v_cndmask_b32_e32 v30, v30, v31, vcc
	v_rsq_f32_e32 v30, v30
	s_nop 0
	v_mul_f32_e32 v31, 0x45800000, v30
	v_cndmask_b32_e32 v30, v30, v31, vcc
	ds_write_b32 v3, v30
	s_waitcnt vmcnt(2)
	v_mov_b32_e32 v46, v35
	v_mov_b32_e32 v47, v36
	v_mov_b32_e32 v35, v37
	v_pk_add_f32 v[34:35], v[46:47], v[34:35]
	s_nop 0
	v_add_f32_e32 v34, v34, v35
	v_fmamk_f32 v34, v34, 0x3a800000, v4
	v_mul_f32_e32 v35, 0x4b800000, v34
	v_cmp_gt_f32_e32 vcc, s0, v34
	s_nop 1
	v_cndmask_b32_e32 v34, v34, v35, vcc
	v_rsq_f32_e32 v34, v34
	s_nop 0
	v_mul_f32_e32 v35, 0x45800000, v34
	v_cndmask_b32_e32 v34, v34, v35, vcc
	ds_write_b32 v3, v34 offset:2048
	s_waitcnt vmcnt(1)
	v_mov_b32_e32 v46, v39
	v_mov_b32_e32 v47, v40
	v_mov_b32_e32 v39, v41
	v_pk_add_f32 v[38:39], v[46:47], v[38:39]
	s_nop 0
	v_add_f32_e32 v38, v38, v39
	v_fmamk_f32 v38, v38, 0x3a800000, v4
	v_mul_f32_e32 v39, 0x4b800000, v38
	v_cmp_gt_f32_e32 vcc, s0, v38
	s_nop 1
	v_cndmask_b32_e32 v38, v38, v39, vcc
	v_rsq_f32_e32 v38, v38
	s_nop 0
	v_mul_f32_e32 v39, 0x45800000, v38
	v_cndmask_b32_e32 v38, v38, v39, vcc
	ds_write_b32 v3, v38 offset:4096
	s_waitcnt vmcnt(0)
	v_mov_b32_e32 v46, v43
	v_mov_b32_e32 v47, v44
	v_mov_b32_e32 v43, v45
	v_pk_add_f32 v[42:43], v[46:47], v[42:43]
	s_nop 0
	v_add_f32_e32 v42, v42, v43
	v_fmamk_f32 v42, v42, 0x3a800000, v4
	v_mul_f32_e32 v43, 0x4b800000, v42
	v_cmp_gt_f32_e32 vcc, s0, v42
	s_nop 1
	v_cndmask_b32_e32 v42, v42, v43, vcc
	v_rsq_f32_e32 v42, v42
	s_nop 0
	v_mul_f32_e32 v43, 0x45800000, v42
	v_cndmask_b32_e32 v42, v42, v43, vcc
	ds_write_b32 v3, v42 offset:6144

; #define LAS __attribute__((address_space(3)))
; __device__ __forceinline__ float row_rs(const float* ssp, int row) { const f32x4 s = *(const f32x4*)(ssp + (size_t)row * 4); return rsqrtf(((s[0] + s[1]) + (s[2] + s[3])) * (1.0f / DM) + RMS_EPS); }
; __device__ __forceinline__ int fill_rs_table(LAS unsigned char* lds, const float* ssp, const pg8::StaticOrder& S, int tid) {
;     pg8::Unit u0; const int row_base = S.next(0, u0) ? (u0.pm / pg8::WGM) * pg8::WGM * pg8::BM : 0;
;     LAS float* rst = (LAS float*)(lds + RST_OFF);
;     for (int i = tid; i < pg8::WGM * pg8::BM; i += NTHREADS) rst[i] = row_rs(ssp, row_base + i);
;     asm volatile("s_waitcnt lgkmcnt(0)" ::: "memory"); __syncthreads();
.LBB0_476:
	global_load_dwordx4 v[30:33], v[0:1], off
	v_lshl_add_u64 v[0:1], v[0:1], 0, s[78:79]
	global_load_dwordx4 v[34:37], v[0:1], off
	v_lshl_add_u64 v[0:1], v[0:1], 0, s[78:79]
	global_load_dwordx4 v[38:41], v[0:1], off
	v_lshl_add_u64 v[0:1], v[0:1], 0, s[78:79]
	global_load_dwordx4 v[42:45], v[0:1], off
	s_waitcnt vmcnt(3)
	v_mov_b32_e32 v46, v31
	v_mov_b32_e32 v47, v32
	v_mov_b32_e32 v31, v33
	v_pk_add_f32 v[30:31], v[46:47], v[30:31]
	s_nop 0
	v_add_f32_e32 v30, v30, v31
	v_fmamk_f32 v30, v30, 0x3a800000, v166
	v_mul_f32_e32 v31, 0x4b800000, v30
	v_cmp_gt_f32_e32 vcc, s40, v30
	s_nop 1
	v_cndmask_b32_e32 v30, v30, v31, vcc
	v_rsq_f32_e32 v30, v30
	s_nop 0
	v_mul_f32_e32 v31, 0x45800000, v30
	v_cndmask_b32_e32 v30, v30, v31, vcc
	ds_write_b32 v3, v30
	s_waitcnt vmcnt(2)
	v_mov_b32_e32 v46, v35
	v_mov_b32_e32 v47, v36
	v_mov_b32_e32 v35, v37
	v_pk_add_f32 v[34:35], v[46:47], v[34:35]
	s_nop 0
	v_add_f32_e32 v34, v34, v35
	v_fmamk_f32 v34, v34, 0x3a800000, v166
	v_mul_f32_e32 v35, 0x4b800000, v34
	v_cmp_gt_f32_e32 vcc, s40, v34
	s_nop 1
	v_cndmask_b32_e32 v34, v34, v35, vcc
	v_rsq_f32_e32 v34, v34
	s_nop 0
	v_mul_f32_e32 v35, 0x45800000, v34
	v_cndmask_b32_e32 v34, v34, v35, vcc
	ds_write_b32 v3, v34 offset:2048
	s_waitcnt vmcnt(1)
	v_mov_b32_e32 v46, v39
	v_mov_b32_e32 v47, v40
	v_mov_b32_e32 v39, v41
	v_pk_add_f32 v[38:39], v[46:47], v[38:39]
	s_nop 0
	v_add_f32_e32 v38, v38, v39
	v_fmamk_f32 v38, v38, 0x3a800000, v166
	v_mul_f32_e32 v39, 0x4b800000, v38
	v_cmp_gt_f32_e32 vcc, s40, v38
	s_nop 1
	v_cndmask_b32_e32 v38, v38, v39, vcc
	v_rsq_f32_e32 v38, v38
	s_nop 0
	v_mul_f32_e32 v39, 0x45800000, v38
	v_cndmask_b32_e32 v38, v38, v39, vcc
	ds_write_b32 v3, v38 offset:4096
	s_waitcnt vmcnt(0)
	v_mov_b32_e32 v46, v43
	v_mov_b32_e32 v47, v44
	v_mov_b32_e32 v43, v45
	v_pk_add_f32 v[42:43], v[46:47], v[42:43]
	s_nop 0
	v_add_f32_e32 v42, v42, v43
	v_fmamk_f32 v42, v42, 0x3a800000, v166
	v_mul_f32_e32 v43, 0x4b800000, v42
	v_cmp_gt_f32_e32 vcc, s40, v42
	s_nop 1
	v_cndmask_b32_e32 v42, v42, v43, vcc
	v_rsq_f32_e32 v42, v42
	s_nop 0
	v_mul_f32_e32 v43, 0x45800000, v42
	v_cndmask_b32_e32 v42, v42, v43, vcc
	ds_write_b32 v3, v42 offset:6144
